# up-GEMM sample-panel epilogue: each row block's two conv-state loads issued one block ahead into dead fragment registers, counted wait leaves the previous block's stores in flight (on top of the K-loo
# speedup vs baseline: 1.0098x; 1.0098x over previous
.LBB0_1713:
	s_and_b64 vcc, exec, s[26:27]
	s_cbranch_vccz .LBB0_1712
	v_lshl_add_u32 v118, v242, 2, 0
	v_add_u32_e32 v110, 0x21000, v118
	v_add_u32_e32 v111, 0x21200, v118
	v_add_u32_e32 v119, 0x21400, v118
	v_add_u32_e32 v118, 0x21600, v118
	ds_read_b128 v[114:117], v110
	ds_read_b128 v[110:113], v111
	ds_read_b128 v[122:125], v119
	ds_read_b128 v[118:121], v118
	v_ashrrev_i32_e32 v207, 31, v206
	s_movk_i32 s19, 0x2080
	v_add_u32_e32 v157, 0xffffe000, v241
	v_cmp_gt_i32_e64 s[36:37], s19, v241
	v_lshlrev_b64 v[154:155], 2, v[206:207]
	v_add_u32_e32 v156, s8, v157
	s_and_saveexec_b64 s[38:39], s[36:37]
	s_cbranch_execz .LBB0_1716
	v_mov_b64_e32 v[146:147], s[60:61]
	s_mov_b32 s19, 0xac00
	v_mad_i64_i32 v[146:147], s[26:27], v157, s19, v[146:147]
	v_lshl_add_u64 v[146:147], v[146:147], 0, v[154:155]
	global_load_dwordx4 v[150:153], v[146:147], off
	v_add_co_u32_e32 v146, vcc, 0x5000, v146
	v_mov_b64_e32 v[158:159], s[66:67]
	s_nop 0
	v_addc_co_u32_e32 v147, vcc, 0, v147, vcc
	global_load_dwordx4 v[146:149], v[146:147], off offset:1536
	s_movk_i32 s100, 0x2070
	v_cmp_gt_i32_e32 vcc, s100, v241
	s_and_saveexec_b64 s[100:101], vcc
	v_add_u32_e32 v246, 0xffffe010, v241
	v_mul_u32_u24_e32 v246, 0xac00, v246
	v_lshl_add_u32 v246, v206, 2, v246
	v_mov_b32_e32 v247, 0
	v_add_u32_e32 v248, 0x5600, v246
	v_mov_b32_e32 v249, 0
	v_lshl_add_u64 v[246:247], v[246:247], 0, s[60:61]
	v_lshl_add_u64 v[248:249], v[248:249], 0, s[60:61]
	global_load_dwordx4 v[170:173], v[246:247], off
	global_load_dwordx4 v[174:177], v[248:249], off
	s_mov_b64 exec, s[100:101]
	v_mad_i64_i32 v[158:159], s[26:27], v156, s19, v[158:159]
	v_lshl_add_u64 v[158:159], v[158:159], 0, v[154:155]
	v_pk_mul_f32 v[144:145], v[144:145], v[222:223] op_sel_hi:[1,0]
	v_pk_mul_f32 v[142:143], v[142:143], v[222:223] op_sel_hi:[1,0]
	s_waitcnt lgkmcnt(0)
	v_mov_b32_e32 v160, v122
	s_movk_i32 s19, 0x2b00
	s_waitcnt vmcnt(2)
	v_fma_f32 v150, v114, v150, v118
	global_store_dwordx4 v[158:159], v[146:149], off
	v_add_co_u32_e32 v158, vcc, 0x5000, v158
	v_mov_b32_e32 v161, v146
	s_nop 0
	v_addc_co_u32_e32 v159, vcc, 0, v159, vcc
	global_store_dwordx4 v[158:159], v[142:145], off offset:1536
	v_mov_b32_e32 v158, v142
	v_mov_b32_e32 v159, v110
	v_pk_mul_f32 v[158:159], v[158:159], v[160:161]
	v_mov_b32_e32 v146, v123
	v_add_f32_e32 v142, v159, v150
	v_add_f32_e32 v159, v158, v142
	v_mul_f32_e32 v142, 0xbfb8aa3b, v159
	v_exp_f32_e32 v142, v142
	v_mov_b32_e32 v158, v138
	v_fma_f32 v138, v115, v151, v119
	v_add_f32_e32 v142, 1.0, v142
	v_rcp_f32_e32 v223, v142
	v_mov_b32_e32 v142, v143
	v_mov_b32_e32 v143, v111
	v_pk_mul_f32 v[142:143], v[142:143], v[146:147]
	v_pk_mul_f32 v[158:159], v[158:159], v[222:223]
	v_add_f32_e32 v138, v143, v138
	v_add_f32_e32 v143, v142, v138
	v_mul_f32_e32 v138, 0xbfb8aa3b, v143
	v_exp_f32_e32 v138, v138
	v_mov_b32_e32 v142, v139
	v_fma_f32 v147, v116, v152, v120
	v_mul_f32_e32 v150, v158, v159
	v_add_f32_e32 v138, 1.0, v138
	v_rcp_f32_e32 v223, v138
	s_nop 0
	v_pk_mul_f32 v[138:139], v[142:143], v[222:223]
	s_nop 0
	v_mul_f32_e32 v146, v138, v139
	v_mov_b32_e32 v138, v144
	v_mov_b32_e32 v139, v112
	v_mov_b32_e32 v142, v124
	v_mov_b32_e32 v143, v148
	v_pk_mul_f32 v[138:139], v[138:139], v[142:143]
	v_mov_b32_e32 v148, v125
	v_add_f32_e32 v139, v139, v147
	v_add_f32_e32 v139, v138, v139
	v_mul_f32_e32 v138, 0xbfb8aa3b, v139
	v_exp_f32_e32 v138, v138
	v_fma_f32 v142, v117, v153, v121
	v_add_f32_e32 v138, 1.0, v138
	v_rcp_f32_e32 v223, v138
	v_mov_b32_e32 v138, v140
	v_pk_mul_f32 v[138:139], v[138:139], v[222:223]
	s_nop 0
	v_mul_f32_e32 v140, v138, v139
	v_mov_b32_e32 v138, v145
	v_mov_b32_e32 v139, v113
	v_pk_mul_f32 v[138:139], v[138:139], v[148:149]
	s_nop 0
	v_add_f32_e32 v139, v139, v142
	v_add_f32_e32 v139, v138, v139
	v_mul_f32_e32 v138, 0xbfb8aa3b, v139
	v_exp_f32_e32 v138, v138
	s_nop 0
	v_add_f32_e32 v138, 1.0, v138
	v_rcp_f32_e32 v223, v138
	v_mov_b32_e32 v138, v141
	v_pk_mul_f32 v[138:139], v[138:139], v[222:223]
	s_nop 0
	v_mul_f32_e32 v139, v138, v139
	v_cvt_pk_bf16_f32 v138, v150, v146
	v_cvt_pk_bf16_f32 v139, v140, v139
	v_mov_b64_e32 v[140:141], s[58:59]
	v_mad_i64_i32 v[140:141], s[26:27], v241, s19, v[140:141]
	v_lshl_add_u64 v[140:141], v[206:207], 1, v[140:141]
	global_store_dwordx2 v[140:141], v[138:139], off
.LBB0_1716:
	s_or_b64 exec, exec, s[38:39]
	s_movk_i32 s19, 0x2070
	v_add_u32_e32 v148, 0xffffe010, v241
	v_add_u32_e32 v146, 16, v241
	v_cmp_gt_i32_e64 s[38:39], s19, v241
	v_add_u32_e32 v147, s8, v148
	s_and_saveexec_b64 s[26:27], s[38:39]
	s_cbranch_execz .LBB0_1718
	v_mov_b64_e32 v[138:139], s[60:61]
	s_mov_b32 s19, 0xac00
	v_mad_i64_i32 v[138:139], s[40:41], v148, s19, v[138:139]
	v_lshl_add_u64 v[138:139], v[138:139], 0, v[154:155]
	v_add_co_u32_e32 v138, vcc, 0x5000, v138
	v_mov_b64_e32 v[150:151], s[66:67]
	s_nop 0
	v_addc_co_u32_e32 v139, vcc, 0, v139, vcc
	s_waitcnt vmcnt(3)
	v_mov_b32_e32 v142, v170
	v_mov_b32_e32 v143, v171
	v_mov_b32_e32 v144, v172
	v_mov_b32_e32 v145, v173
	v_mov_b32_e32 v138, v174
	v_mov_b32_e32 v139, v175
	v_mov_b32_e32 v140, v176
	v_mov_b32_e32 v141, v177
	s_movk_i32 s100, 0x2060
	v_cmp_gt_i32_e32 vcc, s100, v241
	s_and_saveexec_b64 s[100:101], vcc
	v_add_u32_e32 v246, 0xffffe020, v241
	v_mul_u32_u24_e32 v246, 0xac00, v246
	v_lshl_add_u32 v246, v206, 2, v246
	v_mov_b32_e32 v247, 0
	v_add_u32_e32 v248, 0x5600, v246
	v_mov_b32_e32 v249, 0
	v_lshl_add_u64 v[246:247], v[246:247], 0, s[60:61]
	v_lshl_add_u64 v[248:249], v[248:249], 0, s[60:61]
	global_load_dwordx4 v[162:165], v[246:247], off
	global_load_dwordx4 v[166:169], v[248:249], off
	s_mov_b64 exec, s[100:101]
	v_mad_i64_i32 v[150:151], s[40:41], v147, s19, v[150:151]
	v_lshl_add_u64 v[150:151], v[150:151], 0, v[154:155]
	v_pk_mul_f32 v[136:137], v[136:137], v[220:221] op_sel_hi:[1,0]
	v_pk_mul_f32 v[134:135], v[134:135], v[220:221] op_sel_hi:[1,0]
	s_waitcnt lgkmcnt(0)
	v_mov_b32_e32 v152, v122
	s_movk_i32 s19, 0x2b00
	v_fma_f32 v142, v114, v142, v118
	global_store_dwordx4 v[150:151], v[138:141], off
	v_add_co_u32_e32 v150, vcc, 0x5000, v150
	v_mov_b32_e32 v153, v138
	s_nop 0
	v_addc_co_u32_e32 v151, vcc, 0, v151, vcc
	global_store_dwordx4 v[150:151], v[134:137], off offset:1536
	v_mov_b32_e32 v150, v134
	v_mov_b32_e32 v151, v110
	v_pk_mul_f32 v[150:151], v[150:151], v[152:153]
	v_mov_b32_e32 v138, v123
	v_add_f32_e32 v134, v151, v142
	v_add_f32_e32 v151, v150, v134
	v_mul_f32_e32 v134, 0xbfb8aa3b, v151
	v_exp_f32_e32 v134, v134
	v_mov_b32_e32 v150, v130
	v_fma_f32 v130, v115, v143, v119
	v_add_f32_e32 v134, 1.0, v134
	v_rcp_f32_e32 v221, v134
	v_mov_b32_e32 v134, v135
	v_mov_b32_e32 v135, v111
	v_pk_mul_f32 v[134:135], v[134:135], v[138:139]
	v_pk_mul_f32 v[150:151], v[150:151], v[220:221]
	v_add_f32_e32 v130, v135, v130
	v_add_f32_e32 v135, v134, v130
	v_mul_f32_e32 v130, 0xbfb8aa3b, v135
	v_exp_f32_e32 v130, v130
	v_mov_b32_e32 v134, v131
	v_fma_f32 v139, v116, v144, v120
	v_mul_f32_e32 v142, v150, v151
	v_add_f32_e32 v130, 1.0, v130
	v_rcp_f32_e32 v221, v130
	s_nop 0
	v_pk_mul_f32 v[130:131], v[134:135], v[220:221]
	s_nop 0
	v_mul_f32_e32 v138, v130, v131
	v_mov_b32_e32 v130, v136
	v_mov_b32_e32 v131, v112
	v_mov_b32_e32 v134, v124
	v_mov_b32_e32 v135, v140
	v_pk_mul_f32 v[130:131], v[130:131], v[134:135]
	v_mov_b32_e32 v140, v125
	v_add_f32_e32 v131, v131, v139
	v_add_f32_e32 v131, v130, v131
	v_mul_f32_e32 v130, 0xbfb8aa3b, v131
	v_exp_f32_e32 v130, v130
	v_fma_f32 v134, v117, v145, v121
	v_add_f32_e32 v130, 1.0, v130
	v_rcp_f32_e32 v221, v130
	v_mov_b32_e32 v130, v132
	v_pk_mul_f32 v[130:131], v[130:131], v[220:221]
	s_nop 0
	v_mul_f32_e32 v132, v130, v131
	v_mov_b32_e32 v130, v137
	v_mov_b32_e32 v131, v113
	v_pk_mul_f32 v[130:131], v[130:131], v[140:141]
	s_nop 0
	v_add_f32_e32 v131, v131, v134
	v_add_f32_e32 v131, v130, v131
	v_mul_f32_e32 v130, 0xbfb8aa3b, v131
	v_exp_f32_e32 v130, v130
	s_nop 0
	v_add_f32_e32 v130, 1.0, v130
	v_rcp_f32_e32 v221, v130
	v_mov_b32_e32 v130, v133
	v_pk_mul_f32 v[130:131], v[130:131], v[220:221]
	s_nop 0
	v_mul_f32_e32 v131, v130, v131
	v_cvt_pk_bf16_f32 v130, v142, v138
	v_cvt_pk_bf16_f32 v131, v132, v131
	v_mov_b64_e32 v[132:133], s[58:59]
	v_mad_i64_i32 v[132:133], s[40:41], v146, s19, v[132:133]
	v_lshl_add_u64 v[132:133], v[206:207], 1, v[132:133]
	global_store_dwordx2 v[132:133], v[130:131], off
.LBB0_1718:
	s_or_b64 exec, exec, s[26:27]
	s_movk_i32 s19, 0x2060
	v_add_u32_e32 v140, 0xffffe020, v241
	v_add_u32_e32 v138, 32, v241
	v_cmp_gt_i32_e64 s[40:41], s19, v241
	v_add_u32_e32 v139, s8, v140
	s_and_saveexec_b64 s[26:27], s[40:41]
	s_cbranch_execz .LBB0_1720
	v_mov_b64_e32 v[130:131], s[60:61]
	s_mov_b32 s19, 0xac00
	v_mad_i64_i32 v[130:131], s[42:43], v140, s19, v[130:131]
	v_lshl_add_u64 v[130:131], v[130:131], 0, v[154:155]
	v_add_co_u32_e32 v130, vcc, 0x5000, v130
	v_mov_b64_e32 v[142:143], s[66:67]
	s_nop 0
	v_addc_co_u32_e32 v131, vcc, 0, v131, vcc
	s_waitcnt vmcnt(3)
	v_mov_b32_e32 v134, v162
	v_mov_b32_e32 v135, v163
	v_mov_b32_e32 v136, v164
	v_mov_b32_e32 v137, v165
	v_mov_b32_e32 v130, v166
	v_mov_b32_e32 v131, v167
	v_mov_b32_e32 v132, v168
	v_mov_b32_e32 v133, v169
	s_movk_i32 s100, 0x2050
	v_cmp_gt_i32_e32 vcc, s100, v241
	s_and_saveexec_b64 s[100:101], vcc
	v_add_u32_e32 v246, 0xffffe030, v241
	v_mul_u32_u24_e32 v246, 0xac00, v246
	v_lshl_add_u32 v246, v206, 2, v246
	v_mov_b32_e32 v247, 0
	v_add_u32_e32 v248, 0x5600, v246
	v_mov_b32_e32 v249, 0
	v_lshl_add_u64 v[246:247], v[246:247], 0, s[60:61]
	v_lshl_add_u64 v[248:249], v[248:249], 0, s[60:61]
	global_load_dwordx4 v[170:173], v[246:247], off
	global_load_dwordx4 v[174:177], v[248:249], off
	s_mov_b64 exec, s[100:101]
	v_mad_i64_i32 v[142:143], s[42:43], v139, s19, v[142:143]
	v_lshl_add_u64 v[142:143], v[142:143], 0, v[154:155]
	v_pk_mul_f32 v[128:129], v[128:129], v[218:219] op_sel_hi:[1,0]
	v_pk_mul_f32 v[126:127], v[126:127], v[218:219] op_sel_hi:[1,0]
	s_waitcnt lgkmcnt(0)
	v_mov_b32_e32 v144, v122
	s_movk_i32 s19, 0x2b00
	v_fma_f32 v134, v114, v134, v118
	global_store_dwordx4 v[142:143], v[130:133], off
	v_add_co_u32_e32 v142, vcc, 0x5000, v142
	v_mov_b32_e32 v145, v130
	s_nop 0
	v_addc_co_u32_e32 v143, vcc, 0, v143, vcc
	global_store_dwordx4 v[142:143], v[126:129], off offset:1536
	v_mov_b32_e32 v142, v126
	v_mov_b32_e32 v143, v110
	v_pk_mul_f32 v[142:143], v[142:143], v[144:145]
	v_mov_b32_e32 v130, v123
	v_add_f32_e32 v126, v143, v134
	v_add_f32_e32 v143, v142, v126
	v_mul_f32_e32 v126, 0xbfb8aa3b, v143
	v_exp_f32_e32 v126, v126
	v_mov_b32_e32 v142, v106
	v_fma_f32 v106, v115, v135, v119
	v_add_f32_e32 v126, 1.0, v126
	v_rcp_f32_e32 v219, v126
	v_mov_b32_e32 v126, v127
	v_mov_b32_e32 v127, v111
	v_pk_mul_f32 v[126:127], v[126:127], v[130:131]
	v_pk_mul_f32 v[142:143], v[142:143], v[218:219]
	v_add_f32_e32 v106, v127, v106
	v_add_f32_e32 v127, v126, v106
	v_mul_f32_e32 v106, 0xbfb8aa3b, v127
	v_exp_f32_e32 v106, v106
	v_mov_b32_e32 v126, v107
	v_fma_f32 v131, v116, v136, v120
	v_mul_f32_e32 v134, v142, v143
	v_add_f32_e32 v106, 1.0, v106
	v_rcp_f32_e32 v219, v106
	s_nop 0
	v_pk_mul_f32 v[106:107], v[126:127], v[218:219]
	s_nop 0
	v_mul_f32_e32 v130, v106, v107
	v_mov_b32_e32 v106, v128
	v_mov_b32_e32 v107, v112
	v_mov_b32_e32 v126, v124
	v_mov_b32_e32 v127, v132
	v_pk_mul_f32 v[106:107], v[106:107], v[126:127]
	v_mov_b32_e32 v132, v125
	v_add_f32_e32 v107, v107, v131
	v_add_f32_e32 v107, v106, v107
	v_mul_f32_e32 v106, 0xbfb8aa3b, v107
	v_exp_f32_e32 v106, v106
	v_fma_f32 v126, v117, v137, v121
	v_add_f32_e32 v106, 1.0, v106
	v_rcp_f32_e32 v219, v106
	v_mov_b32_e32 v106, v108
	v_pk_mul_f32 v[106:107], v[106:107], v[218:219]
	s_nop 0
	v_mul_f32_e32 v108, v106, v107
	v_mov_b32_e32 v106, v129
	v_mov_b32_e32 v107, v113
	v_pk_mul_f32 v[106:107], v[106:107], v[132:133]
	s_nop 0
	v_add_f32_e32 v107, v107, v126
	v_add_f32_e32 v107, v106, v107
	v_mul_f32_e32 v106, 0xbfb8aa3b, v107
	v_exp_f32_e32 v106, v106
	s_nop 0
	v_add_f32_e32 v106, 1.0, v106
	v_rcp_f32_e32 v219, v106
	v_mov_b32_e32 v106, v109
	v_pk_mul_f32 v[106:107], v[106:107], v[218:219]
	s_nop 0
	v_mul_f32_e32 v107, v106, v107
	v_cvt_pk_bf16_f32 v106, v134, v130
	v_cvt_pk_bf16_f32 v107, v108, v107
	v_mov_b64_e32 v[108:109], s[58:59]
	v_mad_i64_i32 v[108:109], s[42:43], v138, s19, v[108:109]
	v_lshl_add_u64 v[108:109], v[206:207], 1, v[108:109]
	global_store_dwordx2 v[108:109], v[106:107], off
.LBB0_1720:
	s_or_b64 exec, exec, s[26:27]
	s_movk_i32 s19, 0x2050
	v_add_u32_e32 v132, 0xffffe030, v241
	v_add_u32_e32 v130, 48, v241
	v_cmp_gt_i32_e64 s[42:43], s19, v241
	v_add_u32_e32 v131, s8, v132
	s_and_saveexec_b64 s[26:27], s[42:43]
	s_cbranch_execz .LBB0_1722
	v_mov_b64_e32 v[106:107], s[60:61]
	s_mov_b32 s19, 0xac00
	v_mad_i64_i32 v[106:107], s[44:45], v132, s19, v[106:107]
	v_lshl_add_u64 v[106:107], v[106:107], 0, v[154:155]
	v_add_co_u32_e32 v106, vcc, 0x5000, v106
	v_mov_b64_e32 v[134:135], s[66:67]
	s_nop 0
	v_addc_co_u32_e32 v107, vcc, 0, v107, vcc
	s_waitcnt vmcnt(3)
	v_mov_b32_e32 v126, v170
	v_mov_b32_e32 v127, v171
	v_mov_b32_e32 v128, v172
	v_mov_b32_e32 v129, v173
	v_mov_b32_e32 v106, v174
	v_mov_b32_e32 v107, v175
	v_mov_b32_e32 v108, v176
	v_mov_b32_e32 v109, v177
	s_movk_i32 s100, 0x2040
	v_cmp_gt_i32_e32 vcc, s100, v241
	s_and_saveexec_b64 s[100:101], vcc
	v_add_u32_e32 v246, 0xffffe040, v241
	v_mul_u32_u24_e32 v246, 0xac00, v246
	v_lshl_add_u32 v246, v206, 2, v246
	v_mov_b32_e32 v247, 0
	v_add_u32_e32 v248, 0x5600, v246
	v_mov_b32_e32 v249, 0
	v_lshl_add_u64 v[246:247], v[246:247], 0, s[60:61]
	v_lshl_add_u64 v[248:249], v[248:249], 0, s[60:61]
	global_load_dwordx4 v[162:165], v[246:247], off
	global_load_dwordx4 v[166:169], v[248:249], off
	s_mov_b64 exec, s[100:101]
	v_mad_i64_i32 v[134:135], s[44:45], v131, s19, v[134:135]
	v_lshl_add_u64 v[134:135], v[134:135], 0, v[154:155]
	v_pk_mul_f32 v[104:105], v[104:105], v[216:217] op_sel_hi:[1,0]
	v_pk_mul_f32 v[102:103], v[102:103], v[216:217] op_sel_hi:[1,0]
	s_waitcnt lgkmcnt(0)
	v_mov_b32_e32 v136, v122
	s_movk_i32 s19, 0x2b00
	v_fma_f32 v126, v114, v126, v118
	global_store_dwordx4 v[134:135], v[106:109], off
	v_add_co_u32_e32 v134, vcc, 0x5000, v134
	v_mov_b32_e32 v137, v106
	s_nop 0
	v_addc_co_u32_e32 v135, vcc, 0, v135, vcc
	global_store_dwordx4 v[134:135], v[102:105], off offset:1536
	v_mov_b32_e32 v134, v102
	v_mov_b32_e32 v135, v110
	v_pk_mul_f32 v[134:135], v[134:135], v[136:137]
	v_mov_b32_e32 v106, v123
	v_add_f32_e32 v102, v135, v126
	v_add_f32_e32 v135, v134, v102
	v_mul_f32_e32 v102, 0xbfb8aa3b, v135
	v_exp_f32_e32 v102, v102
	v_mov_b32_e32 v134, v98
	v_fma_f32 v98, v115, v127, v119
	v_add_f32_e32 v102, 1.0, v102
	v_rcp_f32_e32 v217, v102
	v_mov_b32_e32 v102, v103
	v_mov_b32_e32 v103, v111
	v_pk_mul_f32 v[102:103], v[102:103], v[106:107]
	v_pk_mul_f32 v[134:135], v[134:135], v[216:217]
	v_add_f32_e32 v98, v103, v98
	v_add_f32_e32 v103, v102, v98
	v_mul_f32_e32 v98, 0xbfb8aa3b, v103
	v_exp_f32_e32 v98, v98
	v_mov_b32_e32 v102, v99
	v_fma_f32 v107, v116, v128, v120
	v_mul_f32_e32 v126, v134, v135
	v_add_f32_e32 v98, 1.0, v98
	v_rcp_f32_e32 v217, v98
	s_nop 0
	v_pk_mul_f32 v[98:99], v[102:103], v[216:217]
	s_nop 0
	v_mul_f32_e32 v106, v98, v99
	v_mov_b32_e32 v98, v104
	v_mov_b32_e32 v99, v112
	v_mov_b32_e32 v102, v124
	v_mov_b32_e32 v103, v108
	v_pk_mul_f32 v[98:99], v[98:99], v[102:103]
	v_mov_b32_e32 v108, v125
	v_add_f32_e32 v99, v99, v107
	v_add_f32_e32 v99, v98, v99
	v_mul_f32_e32 v98, 0xbfb8aa3b, v99
	v_exp_f32_e32 v98, v98
	v_fma_f32 v102, v117, v129, v121
	v_add_f32_e32 v98, 1.0, v98
	v_rcp_f32_e32 v217, v98
	v_mov_b32_e32 v98, v100
	v_pk_mul_f32 v[98:99], v[98:99], v[216:217]
	s_nop 0
	v_mul_f32_e32 v100, v98, v99
	v_mov_b32_e32 v98, v105
	v_mov_b32_e32 v99, v113
	v_pk_mul_f32 v[98:99], v[98:99], v[108:109]
	s_nop 0
	v_add_f32_e32 v99, v99, v102
	v_add_f32_e32 v99, v98, v99
	v_mul_f32_e32 v98, 0xbfb8aa3b, v99
	v_exp_f32_e32 v98, v98
	s_nop 0
	v_add_f32_e32 v98, 1.0, v98
	v_rcp_f32_e32 v217, v98
	v_mov_b32_e32 v98, v101
	v_pk_mul_f32 v[98:99], v[98:99], v[216:217]
	s_nop 0
	v_mul_f32_e32 v99, v98, v99
	v_cvt_pk_bf16_f32 v98, v126, v106
	v_cvt_pk_bf16_f32 v99, v100, v99
	v_mov_b64_e32 v[100:101], s[58:59]
	v_mad_i64_i32 v[100:101], s[44:45], v130, s19, v[100:101]
	v_lshl_add_u64 v[100:101], v[206:207], 1, v[100:101]
	global_store_dwordx2 v[100:101], v[98:99], off
.LBB0_1722:
	s_or_b64 exec, exec, s[26:27]
	s_movk_i32 s19, 0x2000
	v_add_u32_e32 v108, 0xffffe080, v241
	v_add_u32_e32 v106, 0x80, v241
	v_cmp_gt_i32_e64 s[44:45], s19, v241
	v_add_u32_e32 v107, s8, v108
	s_and_saveexec_b64 s[26:27], s[44:45]
	s_cbranch_execz .LBB0_1724
	v_mov_b64_e32 v[98:99], s[60:61]
	s_mov_b32 s19, 0xac00
	v_mad_i64_i32 v[98:99], s[46:47], v108, s19, v[98:99]
	v_lshl_add_u64 v[98:99], v[98:99], 0, v[154:155]
	v_add_co_u32_e32 v98, vcc, 0x5000, v98
	v_mov_b64_e32 v[126:127], s[66:67]
	s_nop 0
	v_addc_co_u32_e32 v99, vcc, 0, v99, vcc
	s_waitcnt vmcnt(3)
	v_mov_b32_e32 v102, v162
	v_mov_b32_e32 v103, v163
	v_mov_b32_e32 v104, v164
	v_mov_b32_e32 v105, v165
	v_mov_b32_e32 v98, v166
	v_mov_b32_e32 v99, v167
	v_mov_b32_e32 v100, v168
	v_mov_b32_e32 v101, v169
	s_movk_i32 s100, 0x2030
	v_cmp_gt_i32_e32 vcc, s100, v241
	s_and_saveexec_b64 s[100:101], vcc
	v_add_u32_e32 v246, 0xffffe050, v241
	v_mul_u32_u24_e32 v246, 0xac00, v246
	v_lshl_add_u32 v246, v206, 2, v246
	v_mov_b32_e32 v247, 0
	v_add_u32_e32 v248, 0x5600, v246
	v_mov_b32_e32 v249, 0
	v_lshl_add_u64 v[246:247], v[246:247], 0, s[60:61]
	v_lshl_add_u64 v[248:249], v[248:249], 0, s[60:61]
	global_load_dwordx4 v[170:173], v[246:247], off
	global_load_dwordx4 v[174:177], v[248:249], off
	s_mov_b64 exec, s[100:101]
	v_mad_i64_i32 v[126:127], s[46:47], v107, s19, v[126:127]
	v_lshl_add_u64 v[126:127], v[126:127], 0, v[154:155]
	v_pk_mul_f32 v[96:97], v[96:97], v[214:215] op_sel_hi:[1,0]
	v_pk_mul_f32 v[94:95], v[94:95], v[214:215] op_sel_hi:[1,0]
	s_waitcnt lgkmcnt(0)
	v_mov_b32_e32 v128, v122
	s_movk_i32 s19, 0x2b00
	v_fma_f32 v102, v114, v102, v118
	global_store_dwordx4 v[126:127], v[98:101], off
	v_add_co_u32_e32 v126, vcc, 0x5000, v126
	v_mov_b32_e32 v129, v98
	s_nop 0
	v_addc_co_u32_e32 v127, vcc, 0, v127, vcc
	global_store_dwordx4 v[126:127], v[94:97], off offset:1536
	v_mov_b32_e32 v126, v94
	v_mov_b32_e32 v127, v110
	v_pk_mul_f32 v[126:127], v[126:127], v[128:129]
	v_mov_b32_e32 v98, v123
	v_add_f32_e32 v94, v127, v102
	v_add_f32_e32 v127, v126, v94
	v_mul_f32_e32 v94, 0xbfb8aa3b, v127
	v_exp_f32_e32 v94, v94
	v_mov_b32_e32 v126, v90
	v_fma_f32 v90, v115, v103, v119
	v_add_f32_e32 v94, 1.0, v94
	v_rcp_f32_e32 v215, v94
	v_mov_b32_e32 v94, v95
	v_mov_b32_e32 v95, v111
	v_pk_mul_f32 v[94:95], v[94:95], v[98:99]
	v_pk_mul_f32 v[126:127], v[126:127], v[214:215]
	v_add_f32_e32 v90, v95, v90
	v_add_f32_e32 v95, v94, v90
	v_mul_f32_e32 v90, 0xbfb8aa3b, v95
	v_exp_f32_e32 v90, v90
	v_mov_b32_e32 v94, v91
	v_fma_f32 v99, v116, v104, v120
	v_mul_f32_e32 v102, v126, v127
	v_add_f32_e32 v90, 1.0, v90
	v_rcp_f32_e32 v215, v90
	s_nop 0
	v_pk_mul_f32 v[90:91], v[94:95], v[214:215]
	s_nop 0
	v_mul_f32_e32 v98, v90, v91
	v_mov_b32_e32 v90, v96
	v_mov_b32_e32 v91, v112
	v_mov_b32_e32 v94, v124
	v_mov_b32_e32 v95, v100
	v_pk_mul_f32 v[90:91], v[90:91], v[94:95]
	v_mov_b32_e32 v100, v125
	v_add_f32_e32 v91, v91, v99
	v_add_f32_e32 v91, v90, v91
	v_mul_f32_e32 v90, 0xbfb8aa3b, v91
	v_exp_f32_e32 v90, v90
	v_fma_f32 v94, v117, v105, v121
	v_add_f32_e32 v90, 1.0, v90
	v_rcp_f32_e32 v215, v90
	v_mov_b32_e32 v90, v92
	v_pk_mul_f32 v[90:91], v[90:91], v[214:215]
	s_nop 0
	v_mul_f32_e32 v92, v90, v91
	v_mov_b32_e32 v90, v97
	v_mov_b32_e32 v91, v113
	v_pk_mul_f32 v[90:91], v[90:91], v[100:101]
	s_nop 0
	v_add_f32_e32 v91, v91, v94
	v_add_f32_e32 v91, v90, v91
	v_mul_f32_e32 v90, 0xbfb8aa3b, v91
	v_exp_f32_e32 v90, v90
	s_nop 0
	v_add_f32_e32 v90, 1.0, v90
	v_rcp_f32_e32 v215, v90
	v_mov_b32_e32 v90, v93
	v_pk_mul_f32 v[90:91], v[90:91], v[214:215]
	s_nop 0
	v_mul_f32_e32 v91, v90, v91
	v_cvt_pk_bf16_f32 v90, v102, v98
	v_cvt_pk_bf16_f32 v91, v92, v91
	v_mov_b64_e32 v[92:93], s[58:59]
	v_mad_i64_i32 v[92:93], s[46:47], v106, s19, v[92:93]
	v_lshl_add_u64 v[92:93], v[206:207], 1, v[92:93]
	global_store_dwordx2 v[92:93], v[90:91], off
.LBB0_1724:
	s_or_b64 exec, exec, s[26:27]
	s_movk_i32 s19, 0x1ff0
	v_add_u32_e32 v100, 0xffffe090, v241
	v_add_u32_e32 v98, 0x90, v241
	v_cmp_gt_i32_e64 s[46:47], s19, v241
	v_add_u32_e32 v99, s8, v100
	s_and_saveexec_b64 s[26:27], s[46:47]
	s_cbranch_execz .LBB0_1726
	v_mov_b64_e32 v[90:91], s[60:61]
	s_mov_b32 s19, 0xac00
	v_mad_i64_i32 v[90:91], s[48:49], v100, s19, v[90:91]
	v_lshl_add_u64 v[90:91], v[90:91], 0, v[154:155]
	v_add_co_u32_e32 v90, vcc, 0x5000, v90
	v_mov_b64_e32 v[102:103], s[66:67]
	s_nop 0
	v_addc_co_u32_e32 v91, vcc, 0, v91, vcc
	s_waitcnt vmcnt(3)
	v_mov_b32_e32 v94, v170
	v_mov_b32_e32 v95, v171
	v_mov_b32_e32 v96, v172
	v_mov_b32_e32 v97, v173
	v_mov_b32_e32 v90, v174
	v_mov_b32_e32 v91, v175
	v_mov_b32_e32 v92, v176
	v_mov_b32_e32 v93, v177
	s_movk_i32 s100, 0x2020
	v_cmp_gt_i32_e32 vcc, s100, v241
	s_and_saveexec_b64 s[100:101], vcc
	v_add_u32_e32 v246, 0xffffe060, v241
	v_mul_u32_u24_e32 v246, 0xac00, v246
	v_lshl_add_u32 v246, v206, 2, v246
	v_mov_b32_e32 v247, 0
	v_add_u32_e32 v248, 0x5600, v246
	v_mov_b32_e32 v249, 0
	v_lshl_add_u64 v[246:247], v[246:247], 0, s[60:61]
	v_lshl_add_u64 v[248:249], v[248:249], 0, s[60:61]
	global_load_dwordx4 v[162:165], v[246:247], off
	global_load_dwordx4 v[166:169], v[248:249], off
	s_mov_b64 exec, s[100:101]
	v_mad_i64_i32 v[102:103], s[48:49], v99, s19, v[102:103]
	v_lshl_add_u64 v[102:103], v[102:103], 0, v[154:155]
	v_pk_mul_f32 v[88:89], v[88:89], v[212:213] op_sel_hi:[1,0]
	v_pk_mul_f32 v[86:87], v[86:87], v[212:213] op_sel_hi:[1,0]
	s_waitcnt lgkmcnt(0)
	v_mov_b32_e32 v104, v122
	s_movk_i32 s19, 0x2b00
	v_fma_f32 v94, v114, v94, v118
	global_store_dwordx4 v[102:103], v[90:93], off
	v_add_co_u32_e32 v102, vcc, 0x5000, v102
	v_mov_b32_e32 v105, v90
	s_nop 0
	v_addc_co_u32_e32 v103, vcc, 0, v103, vcc
	global_store_dwordx4 v[102:103], v[86:89], off offset:1536
	v_mov_b32_e32 v102, v86
	v_mov_b32_e32 v103, v110
	v_pk_mul_f32 v[102:103], v[102:103], v[104:105]
	v_mov_b32_e32 v90, v123
	v_add_f32_e32 v86, v103, v94
	v_add_f32_e32 v103, v102, v86
	v_mul_f32_e32 v86, 0xbfb8aa3b, v103
	v_exp_f32_e32 v86, v86
	v_mov_b32_e32 v102, v82
	v_fma_f32 v82, v115, v95, v119
	v_add_f32_e32 v86, 1.0, v86
	v_rcp_f32_e32 v213, v86
	v_mov_b32_e32 v86, v87
	v_mov_b32_e32 v87, v111
	v_pk_mul_f32 v[86:87], v[86:87], v[90:91]
	v_pk_mul_f32 v[102:103], v[102:103], v[212:213]
	v_add_f32_e32 v82, v87, v82
	v_add_f32_e32 v87, v86, v82
	v_mul_f32_e32 v82, 0xbfb8aa3b, v87
	v_exp_f32_e32 v82, v82
	v_mov_b32_e32 v86, v83
	v_fma_f32 v91, v116, v96, v120
	v_mul_f32_e32 v94, v102, v103
	v_add_f32_e32 v82, 1.0, v82
	v_rcp_f32_e32 v213, v82
	s_nop 0
	v_pk_mul_f32 v[82:83], v[86:87], v[212:213]
	s_nop 0
	v_mul_f32_e32 v90, v82, v83
	v_mov_b32_e32 v82, v88
	v_mov_b32_e32 v83, v112
	v_mov_b32_e32 v86, v124
	v_mov_b32_e32 v87, v92
	v_pk_mul_f32 v[82:83], v[82:83], v[86:87]
	v_mov_b32_e32 v92, v125
	v_add_f32_e32 v83, v83, v91
	v_add_f32_e32 v83, v82, v83
	v_mul_f32_e32 v82, 0xbfb8aa3b, v83
	v_exp_f32_e32 v82, v82
	v_fma_f32 v86, v117, v97, v121
	v_add_f32_e32 v82, 1.0, v82
	v_rcp_f32_e32 v213, v82
	v_mov_b32_e32 v82, v84
	v_pk_mul_f32 v[82:83], v[82:83], v[212:213]
	s_nop 0
	v_mul_f32_e32 v84, v82, v83
	v_mov_b32_e32 v82, v89
	v_mov_b32_e32 v83, v113
	v_pk_mul_f32 v[82:83], v[82:83], v[92:93]
	s_nop 0
	v_add_f32_e32 v83, v83, v86
	v_add_f32_e32 v83, v82, v83
	v_mul_f32_e32 v82, 0xbfb8aa3b, v83
	v_exp_f32_e32 v82, v82
	s_nop 0
	v_add_f32_e32 v82, 1.0, v82
	v_rcp_f32_e32 v213, v82
	v_mov_b32_e32 v82, v85
	v_pk_mul_f32 v[82:83], v[82:83], v[212:213]
	s_nop 0
	v_mul_f32_e32 v83, v82, v83
	v_cvt_pk_bf16_f32 v82, v94, v90
	v_cvt_pk_bf16_f32 v83, v84, v83
	v_mov_b64_e32 v[84:85], s[58:59]
	v_mad_i64_i32 v[84:85], s[48:49], v98, s19, v[84:85]
	v_lshl_add_u64 v[84:85], v[206:207], 1, v[84:85]
	global_store_dwordx2 v[84:85], v[82:83], off
.LBB0_1726:
	s_or_b64 exec, exec, s[26:27]
	s_movk_i32 s19, 0x1fe0
	v_add_u32_e32 v94, 0xffffe0a0, v241
	v_add_u32_e32 v90, 0xa0, v241
	v_cmp_gt_i32_e64 s[48:49], s19, v241
	v_add_u32_e32 v92, s8, v94
	s_and_saveexec_b64 s[26:27], s[48:49]
	s_cbranch_execz .LBB0_1728
	v_mov_b64_e32 v[82:83], s[60:61]
	s_mov_b32 s19, 0xac00
	v_mad_i64_i32 v[82:83], s[50:51], v94, s19, v[82:83]
	v_lshl_add_u64 v[82:83], v[82:83], 0, v[154:155]
	v_add_co_u32_e32 v82, vcc, 0x5000, v82
	v_mov_b64_e32 v[96:97], s[66:67]
	s_nop 0
	v_addc_co_u32_e32 v83, vcc, 0, v83, vcc
	s_waitcnt vmcnt(3)
	v_mov_b32_e32 v86, v162
	v_mov_b32_e32 v87, v163
	v_mov_b32_e32 v88, v164
	v_mov_b32_e32 v89, v165
	v_mov_b32_e32 v82, v166
	v_mov_b32_e32 v83, v167
	v_mov_b32_e32 v84, v168
	v_mov_b32_e32 v85, v169
	s_movk_i32 s100, 0x2010
	v_cmp_gt_i32_e32 vcc, s100, v241
	s_and_saveexec_b64 s[100:101], vcc
	v_add_u32_e32 v246, 0xffffe070, v241
	v_mul_u32_u24_e32 v246, 0xac00, v246
	v_lshl_add_u32 v246, v206, 2, v246
	v_mov_b32_e32 v247, 0
	v_add_u32_e32 v248, 0x5600, v246
	v_mov_b32_e32 v249, 0
	v_lshl_add_u64 v[246:247], v[246:247], 0, s[60:61]
	v_lshl_add_u64 v[248:249], v[248:249], 0, s[60:61]
	global_load_dwordx4 v[170:173], v[246:247], off
	global_load_dwordx4 v[174:177], v[248:249], off
	s_mov_b64 exec, s[100:101]
	v_mad_i64_i32 v[96:97], s[50:51], v92, s19, v[96:97]
	v_lshl_add_u64 v[96:97], v[96:97], 0, v[154:155]
	v_pk_mul_f32 v[80:81], v[80:81], v[210:211] op_sel_hi:[1,0]
	v_pk_mul_f32 v[78:79], v[78:79], v[210:211] op_sel_hi:[1,0]
	s_waitcnt lgkmcnt(0)
	v_mov_b32_e32 v102, v122
	s_movk_i32 s19, 0x2b00
	v_fma_f32 v86, v114, v86, v118
	global_store_dwordx4 v[96:97], v[82:85], off
	v_add_co_u32_e32 v96, vcc, 0x5000, v96
	v_mov_b32_e32 v103, v82
	s_nop 0
	v_addc_co_u32_e32 v97, vcc, 0, v97, vcc
	global_store_dwordx4 v[96:97], v[78:81], off offset:1536
	v_mov_b32_e32 v96, v78
	v_mov_b32_e32 v97, v110
	v_pk_mul_f32 v[96:97], v[96:97], v[102:103]
	v_mov_b32_e32 v82, v123
	v_add_f32_e32 v78, v97, v86
	v_add_f32_e32 v97, v96, v78
	v_mul_f32_e32 v78, 0xbfb8aa3b, v97
	v_exp_f32_e32 v78, v78
	v_mov_b32_e32 v96, v74
	v_fma_f32 v74, v115, v87, v119
	v_add_f32_e32 v78, 1.0, v78
	v_rcp_f32_e32 v211, v78
	v_mov_b32_e32 v78, v79
	v_mov_b32_e32 v79, v111
	v_pk_mul_f32 v[78:79], v[78:79], v[82:83]
	v_pk_mul_f32 v[96:97], v[96:97], v[210:211]
	v_add_f32_e32 v74, v79, v74
	v_add_f32_e32 v79, v78, v74
	v_mul_f32_e32 v74, 0xbfb8aa3b, v79
	v_exp_f32_e32 v74, v74
	v_mov_b32_e32 v78, v75
	v_fma_f32 v83, v116, v88, v120
	v_mul_f32_e32 v86, v96, v97
	v_add_f32_e32 v74, 1.0, v74
	v_rcp_f32_e32 v211, v74
	s_nop 0
	v_pk_mul_f32 v[74:75], v[78:79], v[210:211]
	s_nop 0
	v_mul_f32_e32 v82, v74, v75
	v_mov_b32_e32 v74, v80
	v_mov_b32_e32 v75, v112
	v_mov_b32_e32 v78, v124
	v_mov_b32_e32 v79, v84
	v_pk_mul_f32 v[74:75], v[74:75], v[78:79]
	v_mov_b32_e32 v84, v125
	v_add_f32_e32 v75, v75, v83
	v_add_f32_e32 v75, v74, v75
	v_mul_f32_e32 v74, 0xbfb8aa3b, v75
	v_exp_f32_e32 v74, v74
	v_fma_f32 v78, v117, v89, v121
	v_add_f32_e32 v74, 1.0, v74
	v_rcp_f32_e32 v211, v74
	v_mov_b32_e32 v74, v76
	v_pk_mul_f32 v[74:75], v[74:75], v[210:211]
	s_nop 0
	v_mul_f32_e32 v76, v74, v75
	v_mov_b32_e32 v74, v81
	v_mov_b32_e32 v75, v113
	v_pk_mul_f32 v[74:75], v[74:75], v[84:85]
	s_nop 0
	v_add_f32_e32 v75, v75, v78
	v_add_f32_e32 v75, v74, v75
	v_mul_f32_e32 v74, 0xbfb8aa3b, v75
	v_exp_f32_e32 v74, v74
	s_nop 0
	v_add_f32_e32 v74, 1.0, v74
	v_rcp_f32_e32 v211, v74
	v_mov_b32_e32 v74, v77
	v_pk_mul_f32 v[74:75], v[74:75], v[210:211]
	s_nop 0
	v_mul_f32_e32 v75, v74, v75
	v_cvt_pk_bf16_f32 v74, v86, v82
	v_cvt_pk_bf16_f32 v75, v76, v75
	v_mov_b64_e32 v[76:77], s[58:59]
	v_mad_i64_i32 v[76:77], s[50:51], v90, s19, v[76:77]
	v_lshl_add_u64 v[76:77], v[206:207], 1, v[76:77]
	global_store_dwordx2 v[76:77], v[74:75], off
.LBB0_1728:
	s_or_b64 exec, exec, s[26:27]
	s_movk_i32 s19, 0x1fd0
	v_add_u32_e32 v95, 0xffffe0b0, v241
	v_add_u32_e32 v91, 0xb0, v241
	v_cmp_gt_i32_e64 s[50:51], s19, v241
	v_add_u32_e32 v93, s8, v95
	s_and_saveexec_b64 s[26:27], s[50:51]
	s_cbranch_execz .LBB0_1730
	v_mov_b64_e32 v[74:75], s[60:61]
	s_mov_b32 s19, 0xac00
	v_mad_i64_i32 v[74:75], vcc, v95, s19, v[74:75]
	v_lshl_add_u64 v[78:79], v[74:75], 0, v[154:155]
	v_add_co_u32_e32 v78, vcc, 0x5000, v78
	v_mov_b64_e32 v[82:83], s[66:67]
	s_nop 0
	v_addc_co_u32_e32 v79, vcc, 0, v79, vcc
	s_waitcnt vmcnt(3)
	v_mov_b32_e32 v74, v170
	v_mov_b32_e32 v75, v171
	v_mov_b32_e32 v76, v172
	v_mov_b32_e32 v77, v173
	v_mov_b32_e32 v78, v174
	v_mov_b32_e32 v79, v175
	v_mov_b32_e32 v80, v176
	v_mov_b32_e32 v81, v177
	v_mad_i64_i32 v[82:83], vcc, v93, s19, v[82:83]
	v_lshl_add_u64 v[82:83], v[82:83], 0, v[154:155]
	v_pk_mul_f32 v[72:73], v[72:73], v[208:209] op_sel_hi:[1,0]
	v_pk_mul_f32 v[70:71], v[70:71], v[208:209] op_sel_hi:[1,0]
	s_waitcnt lgkmcnt(0)
	v_mov_b32_e32 v84, v122
	s_movk_i32 s19, 0x2b00
	v_fma_f32 v74, v114, v74, v118
	v_fma_f32 v76, v116, v76, v120
	v_fmac_f32_e32 v121, v117, v77
	global_store_dwordx4 v[82:83], v[78:81], off
	v_add_co_u32_e32 v82, vcc, 0x5000, v82
	v_mov_b32_e32 v85, v78
	s_nop 0
	v_addc_co_u32_e32 v83, vcc, 0, v83, vcc
	global_store_dwordx4 v[82:83], v[70:73], off offset:1536
	v_mov_b32_e32 v82, v70
	v_mov_b32_e32 v83, v110
	v_pk_mul_f32 v[82:83], v[82:83], v[84:85]
	v_mov_b32_e32 v110, v71
	v_add_f32_e32 v70, v83, v74
	v_add_f32_e32 v83, v82, v70
	v_mul_f32_e32 v70, 0xbfb8aa3b, v83
	v_exp_f32_e32 v70, v70
	v_mov_b32_e32 v78, v123
	v_mov_b32_e32 v82, v66
	v_fma_f32 v66, v115, v75, v119
	v_add_f32_e32 v70, 1.0, v70
	v_rcp_f32_e32 v209, v70
	v_pk_mul_f32 v[70:71], v[110:111], v[78:79]
	v_pk_mul_f32 v[82:83], v[82:83], v[208:209]
	v_add_f32_e32 v66, v71, v66
	v_add_f32_e32 v71, v70, v66
	v_mul_f32_e32 v66, 0xbfb8aa3b, v71
	v_exp_f32_e32 v66, v66
	v_mov_b32_e32 v70, v67
	v_mul_f32_e32 v74, v82, v83
	v_add_f32_e32 v66, 1.0, v66
	v_rcp_f32_e32 v209, v66
	s_nop 0
	v_pk_mul_f32 v[66:67], v[70:71], v[208:209]
	s_nop 0
	v_mul_f32_e32 v75, v66, v67
	v_mov_b32_e32 v66, v72
	v_mov_b32_e32 v67, v112
	v_mov_b32_e32 v70, v124
	v_mov_b32_e32 v71, v80
	v_pk_mul_f32 v[66:67], v[66:67], v[70:71]
	v_mov_b32_e32 v112, v73
	v_add_f32_e32 v67, v67, v76
	v_add_f32_e32 v67, v66, v67
	v_mul_f32_e32 v66, 0xbfb8aa3b, v67
	v_exp_f32_e32 v66, v66
	v_mov_b32_e32 v80, v125
	v_add_f32_e32 v66, 1.0, v66
	v_rcp_f32_e32 v209, v66
	v_mov_b32_e32 v66, v68
	v_pk_mul_f32 v[66:67], v[66:67], v[208:209]
	s_nop 0
	v_mul_f32_e32 v68, v66, v67
	v_pk_mul_f32 v[66:67], v[112:113], v[80:81]
	s_nop 0
	v_add_f32_e32 v67, v67, v121
	v_add_f32_e32 v67, v66, v67
	v_mul_f32_e32 v66, 0xbfb8aa3b, v67
	v_exp_f32_e32 v66, v66
	s_nop 0
	v_add_f32_e32 v66, 1.0, v66
	v_rcp_f32_e32 v209, v66
	v_mov_b32_e32 v66, v69
	v_pk_mul_f32 v[66:67], v[66:67], v[208:209]
	s_nop 0
	v_mul_f32_e32 v67, v66, v67
	v_cvt_pk_bf16_f32 v66, v74, v75
	v_cvt_pk_bf16_f32 v67, v68, v67
	v_mov_b64_e32 v[68:69], s[58:59]
	v_mad_i64_i32 v[68:69], vcc, v91, s19, v[68:69]
	v_lshl_add_u64 v[68:69], v[206:207], 1, v[68:69]
	global_store_dwordx2 v[68:69], v[66:67], off
.LBB0_1730:
	s_or_b64 exec, exec, s[26:27]
	s_add_i32 s19, 0, 0x20000
	v_lshl_add_u32 v70, v242, 2, s19
	ds_read_b128 v[74:77], v70 offset:4112
	ds_read_b128 v[66:69], v70 offset:4624
	ds_read_b128 v[78:81], v70 offset:5136
	ds_read_b128 v[70:73], v70 offset:5648
	s_and_saveexec_b64 s[26:27], s[36:37]
	s_cbranch_execz .LBB0_1738
	v_mov_b64_e32 v[82:83], s[60:61]
	s_mov_b32 s19, 0xac00
	v_mad_i64_i32 v[82:83], s[36:37], v157, s19, v[82:83]
	v_lshl_add_u64 v[82:83], v[82:83], 0, v[154:155]
	global_load_dwordx4 v[86:89], v[82:83], off offset:16
	v_add_co_u32_e32 v82, vcc, 0x5000, v82
	v_mov_b64_e32 v[96:97], s[66:67]
	s_nop 0
	v_addc_co_u32_e32 v83, vcc, 0, v83, vcc
	global_load_dwordx4 v[82:85], v[82:83], off offset:1552
	s_and_saveexec_b64 s[100:101], s[38:39]
	v_add_u32_e32 v246, 0xffffe010, v241
	v_mul_u32_u24_e32 v246, 0xac00, v246
	v_lshl_add_u32 v246, v206, 2, v246
	v_mov_b32_e32 v247, 0
	v_add_u32_e32 v248, 0x5600, v246
	v_mov_b32_e32 v249, 0
	v_lshl_add_u64 v[246:247], v[246:247], 0, s[60:61]
	v_lshl_add_u64 v[248:249], v[248:249], 0, s[60:61]
	global_load_dwordx4 v[170:173], v[246:247], off offset:16
	global_load_dwordx4 v[174:177], v[248:249], off offset:16
	s_mov_b64 exec, s[100:101]
	v_mad_i64_i32 v[96:97], s[36:37], v156, s19, v[96:97]
	v_lshl_add_u64 v[96:97], v[96:97], 0, v[154:155]
	v_pk_mul_f32 v[64:65], v[64:65], v[222:223] op_sel_hi:[1,0]
	v_pk_mul_f32 v[62:63], v[62:63], v[222:223] op_sel_hi:[1,0]
	s_waitcnt lgkmcnt(0)
	v_mov_b32_e32 v102, v78
	s_movk_i32 s19, 0x2b00
	s_waitcnt vmcnt(2)
	v_fma_f32 v86, v74, v86, v70
	global_store_dwordx4 v[96:97], v[82:85], off offset:16
	v_add_co_u32_e32 v96, vcc, 0x5000, v96
	v_mov_b32_e32 v103, v82
	s_nop 0
	v_addc_co_u32_e32 v97, vcc, 0, v97, vcc
	global_store_dwordx4 v[96:97], v[62:65], off offset:1552
	v_mov_b32_e32 v96, v62
	v_mov_b32_e32 v97, v66
	v_pk_mul_f32 v[96:97], v[96:97], v[102:103]
	v_mov_b32_e32 v82, v79
	v_add_f32_e32 v62, v97, v86
	v_add_f32_e32 v97, v96, v62
	v_mul_f32_e32 v62, 0xbfb8aa3b, v97
	v_exp_f32_e32 v62, v62
	v_mov_b32_e32 v96, v58
	v_fma_f32 v58, v75, v87, v71
	v_add_f32_e32 v62, 1.0, v62
	v_rcp_f32_e32 v223, v62
	v_mov_b32_e32 v62, v63
	v_mov_b32_e32 v63, v67
	v_pk_mul_f32 v[62:63], v[62:63], v[82:83]
	v_pk_mul_f32 v[96:97], v[96:97], v[222:223]
	v_add_f32_e32 v58, v63, v58
	v_add_f32_e32 v63, v62, v58
	v_mul_f32_e32 v58, 0xbfb8aa3b, v63
	v_exp_f32_e32 v58, v58
	v_mov_b32_e32 v62, v59
	v_fma_f32 v83, v76, v88, v72
	v_mul_f32_e32 v86, v96, v97
	v_add_f32_e32 v58, 1.0, v58
	v_rcp_f32_e32 v223, v58
	s_nop 0
	v_pk_mul_f32 v[58:59], v[62:63], v[222:223]
	s_nop 0
	v_mul_f32_e32 v82, v58, v59
	v_mov_b32_e32 v58, v64
	v_mov_b32_e32 v59, v68
	v_mov_b32_e32 v62, v80
	v_mov_b32_e32 v63, v84
	v_pk_mul_f32 v[58:59], v[58:59], v[62:63]
	v_mov_b32_e32 v84, v81
	v_add_f32_e32 v59, v59, v83
	v_add_f32_e32 v59, v58, v59
	v_mul_f32_e32 v58, 0xbfb8aa3b, v59
	v_exp_f32_e32 v58, v58
	v_fma_f32 v62, v77, v89, v73
	v_add_f32_e32 v58, 1.0, v58
	v_rcp_f32_e32 v223, v58
	v_mov_b32_e32 v58, v60
	v_pk_mul_f32 v[58:59], v[58:59], v[222:223]
	s_nop 0
	v_mul_f32_e32 v60, v58, v59
	v_mov_b32_e32 v58, v65
	v_mov_b32_e32 v59, v69
	v_pk_mul_f32 v[58:59], v[58:59], v[84:85]
	s_nop 0
	v_add_f32_e32 v59, v59, v62
	v_add_f32_e32 v59, v58, v59
	v_mul_f32_e32 v58, 0xbfb8aa3b, v59
	v_exp_f32_e32 v58, v58
	s_nop 0
	v_add_f32_e32 v58, 1.0, v58
	v_rcp_f32_e32 v223, v58
	v_mov_b32_e32 v58, v61
	v_pk_mul_f32 v[58:59], v[58:59], v[222:223]
	s_nop 0
	v_mul_f32_e32 v59, v58, v59
	v_cvt_pk_bf16_f32 v58, v86, v82
	v_cvt_pk_bf16_f32 v59, v60, v59
	v_mov_b64_e32 v[60:61], s[58:59]
	v_mad_i64_i32 v[60:61], s[36:37], v241, s19, v[60:61]
	v_lshl_add_u64 v[60:61], v[206:207], 1, v[60:61]
	global_store_dwordx2 v[60:61], v[58:59], off offset:8
	s_or_b64 exec, exec, s[26:27]
	s_and_saveexec_b64 s[26:27], s[38:39]
	s_cbranch_execnz .LBB0_1739

.LBB0_1733:
	v_mov_b64_e32 v[50:51], s[60:61]
	s_mov_b32 s19, 0xac00
	v_mad_i64_i32 v[50:51], s[36:37], v140, s19, v[50:51]
	v_lshl_add_u64 v[50:51], v[50:51], 0, v[154:155]
	v_add_co_u32_e32 v50, vcc, 0x5000, v50
	v_mov_b64_e32 v[58:59], s[66:67]
	s_nop 0
	v_addc_co_u32_e32 v51, vcc, 0, v51, vcc
	s_waitcnt vmcnt(3)
	v_mov_b32_e32 v54, v162
	v_mov_b32_e32 v55, v163
	v_mov_b32_e32 v56, v164
	v_mov_b32_e32 v57, v165
	v_mov_b32_e32 v50, v166
	v_mov_b32_e32 v51, v167
	v_mov_b32_e32 v52, v168
	v_mov_b32_e32 v53, v169
	s_and_saveexec_b64 s[100:101], s[42:43]
	v_add_u32_e32 v246, 0xffffe030, v241
	v_mul_u32_u24_e32 v246, 0xac00, v246
	v_lshl_add_u32 v246, v206, 2, v246
	v_mov_b32_e32 v247, 0
	v_add_u32_e32 v248, 0x5600, v246
	v_mov_b32_e32 v249, 0
	v_lshl_add_u64 v[246:247], v[246:247], 0, s[60:61]
	v_lshl_add_u64 v[248:249], v[248:249], 0, s[60:61]
	global_load_dwordx4 v[170:173], v[246:247], off offset:16
	global_load_dwordx4 v[174:177], v[248:249], off offset:16
	s_mov_b64 exec, s[100:101]
	v_mad_i64_i32 v[58:59], s[36:37], v139, s19, v[58:59]
	v_lshl_add_u64 v[58:59], v[58:59], 0, v[154:155]
	v_pk_mul_f32 v[48:49], v[48:49], v[218:219] op_sel_hi:[1,0]
	v_pk_mul_f32 v[46:47], v[46:47], v[218:219] op_sel_hi:[1,0]
	s_waitcnt lgkmcnt(0)
	v_mov_b32_e32 v60, v78
	s_movk_i32 s19, 0x2b00
	v_fma_f32 v54, v74, v54, v70
	global_store_dwordx4 v[58:59], v[50:53], off offset:16
	v_add_co_u32_e32 v58, vcc, 0x5000, v58
	v_mov_b32_e32 v61, v50
	s_nop 0
	v_addc_co_u32_e32 v59, vcc, 0, v59, vcc
	global_store_dwordx4 v[58:59], v[46:49], off offset:1552
	v_mov_b32_e32 v58, v46
	v_mov_b32_e32 v59, v66
	v_pk_mul_f32 v[58:59], v[58:59], v[60:61]
	v_mov_b32_e32 v50, v79
	v_add_f32_e32 v46, v59, v54
	v_add_f32_e32 v59, v58, v46
	v_mul_f32_e32 v46, 0xbfb8aa3b, v59
	v_exp_f32_e32 v46, v46
	v_mov_b32_e32 v58, v42
	v_fma_f32 v42, v75, v55, v71
	v_add_f32_e32 v46, 1.0, v46
	v_rcp_f32_e32 v219, v46
	v_mov_b32_e32 v46, v47
	v_mov_b32_e32 v47, v67
	v_pk_mul_f32 v[46:47], v[46:47], v[50:51]
	v_pk_mul_f32 v[58:59], v[58:59], v[218:219]
	v_add_f32_e32 v42, v47, v42
	v_add_f32_e32 v47, v46, v42
	v_mul_f32_e32 v42, 0xbfb8aa3b, v47
	v_exp_f32_e32 v42, v42
	v_mov_b32_e32 v46, v43
	v_fma_f32 v51, v76, v56, v72
	v_mul_f32_e32 v54, v58, v59
	v_add_f32_e32 v42, 1.0, v42
	v_rcp_f32_e32 v219, v42
	s_nop 0
	v_pk_mul_f32 v[42:43], v[46:47], v[218:219]
	s_nop 0
	v_mul_f32_e32 v50, v42, v43
	v_mov_b32_e32 v42, v48
	v_mov_b32_e32 v43, v68
	v_mov_b32_e32 v46, v80
	v_mov_b32_e32 v47, v52
	v_pk_mul_f32 v[42:43], v[42:43], v[46:47]
	v_mov_b32_e32 v52, v81
	v_add_f32_e32 v43, v43, v51
	v_add_f32_e32 v43, v42, v43
	v_mul_f32_e32 v42, 0xbfb8aa3b, v43
	v_exp_f32_e32 v42, v42
	v_fma_f32 v46, v77, v57, v73
	v_add_f32_e32 v42, 1.0, v42
	v_rcp_f32_e32 v219, v42
	v_mov_b32_e32 v42, v44
	v_pk_mul_f32 v[42:43], v[42:43], v[218:219]
	s_nop 0
	v_mul_f32_e32 v44, v42, v43
	v_mov_b32_e32 v42, v49
	v_mov_b32_e32 v43, v69
	v_pk_mul_f32 v[42:43], v[42:43], v[52:53]
	s_nop 0
	v_add_f32_e32 v43, v43, v46
	v_add_f32_e32 v43, v42, v43
	v_mul_f32_e32 v42, 0xbfb8aa3b, v43
	v_exp_f32_e32 v42, v42
	s_nop 0
	v_add_f32_e32 v42, 1.0, v42
	v_rcp_f32_e32 v219, v42
	v_mov_b32_e32 v42, v45
	v_pk_mul_f32 v[42:43], v[42:43], v[218:219]
	s_nop 0
	v_mul_f32_e32 v43, v42, v43
	v_cvt_pk_bf16_f32 v42, v54, v50
	v_cvt_pk_bf16_f32 v43, v44, v43
	v_mov_b64_e32 v[44:45], s[58:59]
	v_mad_i64_i32 v[44:45], s[36:37], v138, s19, v[44:45]
	v_lshl_add_u64 v[44:45], v[206:207], 1, v[44:45]
	global_store_dwordx2 v[44:45], v[42:43], off offset:8
	s_or_b64 exec, exec, s[26:27]
	s_and_saveexec_b64 s[26:27], s[42:43]
	s_cbranch_execnz .LBB0_1741

.LBB0_1735:
	v_mov_b64_e32 v[34:35], s[60:61]
	s_mov_b32 s19, 0xac00
	v_mad_i64_i32 v[34:35], s[36:37], v108, s19, v[34:35]
	v_lshl_add_u64 v[34:35], v[34:35], 0, v[154:155]
	v_add_co_u32_e32 v34, vcc, 0x5000, v34
	v_mov_b64_e32 v[42:43], s[66:67]
	s_nop 0
	v_addc_co_u32_e32 v35, vcc, 0, v35, vcc
	s_waitcnt vmcnt(3)
	v_mov_b32_e32 v38, v162
	v_mov_b32_e32 v39, v163
	v_mov_b32_e32 v40, v164
	v_mov_b32_e32 v41, v165
	v_mov_b32_e32 v34, v166
	v_mov_b32_e32 v35, v167
	v_mov_b32_e32 v36, v168
	v_mov_b32_e32 v37, v169
	s_and_saveexec_b64 s[100:101], s[46:47]
	v_add_u32_e32 v246, 0xffffe050, v241
	v_mul_u32_u24_e32 v246, 0xac00, v246
	v_lshl_add_u32 v246, v206, 2, v246
	v_mov_b32_e32 v247, 0
	v_add_u32_e32 v248, 0x5600, v246
	v_mov_b32_e32 v249, 0
	v_lshl_add_u64 v[246:247], v[246:247], 0, s[60:61]
	v_lshl_add_u64 v[248:249], v[248:249], 0, s[60:61]
	global_load_dwordx4 v[170:173], v[246:247], off offset:16
	global_load_dwordx4 v[174:177], v[248:249], off offset:16
	s_mov_b64 exec, s[100:101]
	v_mad_i64_i32 v[42:43], s[36:37], v107, s19, v[42:43]
	v_lshl_add_u64 v[42:43], v[42:43], 0, v[154:155]
	v_pk_mul_f32 v[32:33], v[32:33], v[214:215] op_sel_hi:[1,0]
	v_pk_mul_f32 v[30:31], v[30:31], v[214:215] op_sel_hi:[1,0]
	s_waitcnt lgkmcnt(0)
	v_mov_b32_e32 v44, v78
	s_movk_i32 s19, 0x2b00
	v_fma_f32 v38, v74, v38, v70
	global_store_dwordx4 v[42:43], v[34:37], off offset:16
	v_add_co_u32_e32 v42, vcc, 0x5000, v42
	v_mov_b32_e32 v45, v34
	s_nop 0
	v_addc_co_u32_e32 v43, vcc, 0, v43, vcc
	global_store_dwordx4 v[42:43], v[30:33], off offset:1552
	v_mov_b32_e32 v42, v30
	v_mov_b32_e32 v43, v66
	v_pk_mul_f32 v[42:43], v[42:43], v[44:45]
	v_mov_b32_e32 v34, v79
	v_add_f32_e32 v30, v43, v38
	v_add_f32_e32 v43, v42, v30
	v_mul_f32_e32 v30, 0xbfb8aa3b, v43
	v_exp_f32_e32 v30, v30
	v_mov_b32_e32 v42, v26
	v_fma_f32 v26, v75, v39, v71
	v_add_f32_e32 v30, 1.0, v30
	v_rcp_f32_e32 v215, v30
	v_mov_b32_e32 v30, v31
	v_mov_b32_e32 v31, v67
	v_pk_mul_f32 v[30:31], v[30:31], v[34:35]
	v_pk_mul_f32 v[42:43], v[42:43], v[214:215]
	v_add_f32_e32 v26, v31, v26
	v_add_f32_e32 v31, v30, v26
	v_mul_f32_e32 v26, 0xbfb8aa3b, v31
	v_exp_f32_e32 v26, v26
	v_mov_b32_e32 v30, v27
	v_fma_f32 v35, v76, v40, v72
	v_mul_f32_e32 v38, v42, v43
	v_add_f32_e32 v26, 1.0, v26
	v_rcp_f32_e32 v215, v26
	s_nop 0
	v_pk_mul_f32 v[26:27], v[30:31], v[214:215]
	s_nop 0
	v_mul_f32_e32 v34, v26, v27
	v_mov_b32_e32 v26, v32
	v_mov_b32_e32 v27, v68
	v_mov_b32_e32 v30, v80
	v_mov_b32_e32 v31, v36
	v_pk_mul_f32 v[26:27], v[26:27], v[30:31]
	v_mov_b32_e32 v36, v81
	v_add_f32_e32 v27, v27, v35
	v_add_f32_e32 v27, v26, v27
	v_mul_f32_e32 v26, 0xbfb8aa3b, v27
	v_exp_f32_e32 v26, v26
	v_fma_f32 v30, v77, v41, v73
	v_add_f32_e32 v26, 1.0, v26
	v_rcp_f32_e32 v215, v26
	v_mov_b32_e32 v26, v28
	v_pk_mul_f32 v[26:27], v[26:27], v[214:215]
	s_nop 0
	v_mul_f32_e32 v28, v26, v27
	v_mov_b32_e32 v26, v33
	v_mov_b32_e32 v27, v69
	v_pk_mul_f32 v[26:27], v[26:27], v[36:37]
	s_nop 0
	v_add_f32_e32 v27, v27, v30
	v_add_f32_e32 v27, v26, v27
	v_mul_f32_e32 v26, 0xbfb8aa3b, v27
	v_exp_f32_e32 v26, v26
	s_nop 0
	v_add_f32_e32 v26, 1.0, v26
	v_rcp_f32_e32 v215, v26
	v_mov_b32_e32 v26, v29
	v_pk_mul_f32 v[26:27], v[26:27], v[214:215]
	s_nop 0
	v_mul_f32_e32 v27, v26, v27
	v_cvt_pk_bf16_f32 v26, v38, v34
	v_cvt_pk_bf16_f32 v27, v28, v27
	v_mov_b64_e32 v[28:29], s[58:59]
	v_mad_i64_i32 v[28:29], s[36:37], v106, s19, v[28:29]
	v_lshl_add_u64 v[28:29], v[206:207], 1, v[28:29]
	global_store_dwordx2 v[28:29], v[26:27], off offset:8
	s_or_b64 exec, exec, s[26:27]
	s_and_saveexec_b64 s[26:27], s[46:47]
	s_cbranch_execnz .LBB0_1743

.LBB0_1737:
	v_mov_b64_e32 v[18:19], s[60:61]
	s_mov_b32 s19, 0xac00
	v_mad_i64_i32 v[18:19], s[36:37], v94, s19, v[18:19]
	v_lshl_add_u64 v[18:19], v[18:19], 0, v[154:155]
	v_add_co_u32_e32 v18, vcc, 0x5000, v18
	v_mov_b64_e32 v[26:27], s[66:67]
	s_nop 0
	v_addc_co_u32_e32 v19, vcc, 0, v19, vcc
	s_waitcnt vmcnt(3)
	v_mov_b32_e32 v22, v162
	v_mov_b32_e32 v23, v163
	v_mov_b32_e32 v24, v164
	v_mov_b32_e32 v25, v165
	v_mov_b32_e32 v18, v166
	v_mov_b32_e32 v19, v167
	v_mov_b32_e32 v20, v168
	v_mov_b32_e32 v21, v169
	s_and_saveexec_b64 s[100:101], s[50:51]
	v_add_u32_e32 v246, 0xffffe070, v241
	v_mul_u32_u24_e32 v246, 0xac00, v246
	v_lshl_add_u32 v246, v206, 2, v246
	v_mov_b32_e32 v247, 0
	v_add_u32_e32 v248, 0x5600, v246
	v_mov_b32_e32 v249, 0
	v_lshl_add_u64 v[246:247], v[246:247], 0, s[60:61]
	v_lshl_add_u64 v[248:249], v[248:249], 0, s[60:61]
	global_load_dwordx4 v[170:173], v[246:247], off offset:16
	global_load_dwordx4 v[174:177], v[248:249], off offset:16
	s_mov_b64 exec, s[100:101]
	v_mad_i64_i32 v[26:27], s[36:37], v92, s19, v[26:27]
	v_lshl_add_u64 v[26:27], v[26:27], 0, v[154:155]
	v_pk_mul_f32 v[16:17], v[16:17], v[210:211] op_sel_hi:[1,0]
	v_pk_mul_f32 v[14:15], v[14:15], v[210:211] op_sel_hi:[1,0]
	s_waitcnt lgkmcnt(0)
	v_mov_b32_e32 v28, v78
	s_movk_i32 s19, 0x2b00
	v_fma_f32 v22, v74, v22, v70
	global_store_dwordx4 v[26:27], v[18:21], off offset:16
	v_add_co_u32_e32 v26, vcc, 0x5000, v26
	v_mov_b32_e32 v29, v18
	s_nop 0
	v_addc_co_u32_e32 v27, vcc, 0, v27, vcc
	global_store_dwordx4 v[26:27], v[14:17], off offset:1552
	v_mov_b32_e32 v26, v14
	v_mov_b32_e32 v27, v66
	v_pk_mul_f32 v[26:27], v[26:27], v[28:29]
	v_mov_b32_e32 v18, v79
	v_add_f32_e32 v14, v27, v22
	v_add_f32_e32 v27, v26, v14
	v_mul_f32_e32 v14, 0xbfb8aa3b, v27
	v_exp_f32_e32 v14, v14
	v_mov_b32_e32 v26, v10
	v_fma_f32 v10, v75, v23, v71
	v_add_f32_e32 v14, 1.0, v14
	v_rcp_f32_e32 v211, v14
	v_mov_b32_e32 v14, v15
	v_mov_b32_e32 v15, v67
	v_pk_mul_f32 v[14:15], v[14:15], v[18:19]
	v_pk_mul_f32 v[26:27], v[26:27], v[210:211]
	v_add_f32_e32 v10, v15, v10
	v_add_f32_e32 v15, v14, v10
	v_mul_f32_e32 v10, 0xbfb8aa3b, v15
	v_exp_f32_e32 v10, v10
	v_mov_b32_e32 v14, v11
	v_fma_f32 v19, v76, v24, v72
	v_mul_f32_e32 v22, v26, v27
	v_add_f32_e32 v10, 1.0, v10
	v_rcp_f32_e32 v211, v10
	s_nop 0
	v_pk_mul_f32 v[10:11], v[14:15], v[210:211]
	s_nop 0
	v_mul_f32_e32 v18, v10, v11
	v_mov_b32_e32 v10, v16
	v_mov_b32_e32 v11, v68
	v_mov_b32_e32 v14, v80
	v_mov_b32_e32 v15, v20
	v_pk_mul_f32 v[10:11], v[10:11], v[14:15]
	v_mov_b32_e32 v20, v81
	v_add_f32_e32 v11, v11, v19
	v_add_f32_e32 v11, v10, v11
	v_mul_f32_e32 v10, 0xbfb8aa3b, v11
	v_exp_f32_e32 v10, v10
	v_fma_f32 v14, v77, v25, v73
	v_add_f32_e32 v10, 1.0, v10
	v_rcp_f32_e32 v211, v10
	v_mov_b32_e32 v10, v12
	v_pk_mul_f32 v[10:11], v[10:11], v[210:211]
	s_nop 0
	v_mul_f32_e32 v12, v10, v11
	v_mov_b32_e32 v10, v17
	v_mov_b32_e32 v11, v69
	v_pk_mul_f32 v[10:11], v[10:11], v[20:21]
	s_nop 0
	v_add_f32_e32 v11, v11, v14
	v_add_f32_e32 v11, v10, v11
	v_mul_f32_e32 v10, 0xbfb8aa3b, v11
	v_exp_f32_e32 v10, v10
	s_nop 0
	v_add_f32_e32 v10, 1.0, v10
	v_rcp_f32_e32 v211, v10
	v_mov_b32_e32 v10, v13
	v_pk_mul_f32 v[10:11], v[10:11], v[210:211]
	s_nop 0
	v_mul_f32_e32 v11, v10, v11
	v_cvt_pk_bf16_f32 v10, v22, v18
	v_cvt_pk_bf16_f32 v11, v12, v11
	v_mov_b64_e32 v[12:13], s[58:59]
	v_mad_i64_i32 v[12:13], s[36:37], v90, s19, v[12:13]
	v_lshl_add_u64 v[12:13], v[206:207], 1, v[12:13]
	global_store_dwordx2 v[12:13], v[10:11], off offset:8
	s_or_b64 exec, exec, s[26:27]
	s_and_saveexec_b64 s[26:27], s[50:51]
	s_cbranch_execnz .LBB0_1745
	s_branch .LBB0_1746

.LBB0_1739:
	v_mov_b64_e32 v[58:59], s[60:61]
	s_mov_b32 s19, 0xac00
	v_mad_i64_i32 v[58:59], s[36:37], v148, s19, v[58:59]
	v_lshl_add_u64 v[58:59], v[58:59], 0, v[154:155]
	v_add_co_u32_e32 v58, vcc, 0x5000, v58
	v_mov_b64_e32 v[82:83], s[66:67]
	s_nop 0
	v_addc_co_u32_e32 v59, vcc, 0, v59, vcc
	s_waitcnt vmcnt(3)
	v_mov_b32_e32 v62, v170
	v_mov_b32_e32 v63, v171
	v_mov_b32_e32 v64, v172
	v_mov_b32_e32 v65, v173
	v_mov_b32_e32 v58, v174
	v_mov_b32_e32 v59, v175
	v_mov_b32_e32 v60, v176
	v_mov_b32_e32 v61, v177
	s_and_saveexec_b64 s[100:101], s[40:41]
	v_add_u32_e32 v246, 0xffffe020, v241
	v_mul_u32_u24_e32 v246, 0xac00, v246
	v_lshl_add_u32 v246, v206, 2, v246
	v_mov_b32_e32 v247, 0
	v_add_u32_e32 v248, 0x5600, v246
	v_mov_b32_e32 v249, 0
	v_lshl_add_u64 v[246:247], v[246:247], 0, s[60:61]
	v_lshl_add_u64 v[248:249], v[248:249], 0, s[60:61]
	global_load_dwordx4 v[162:165], v[246:247], off offset:16
	global_load_dwordx4 v[166:169], v[248:249], off offset:16
	s_mov_b64 exec, s[100:101]
	v_mad_i64_i32 v[82:83], s[36:37], v147, s19, v[82:83]
	v_lshl_add_u64 v[82:83], v[82:83], 0, v[154:155]
	v_pk_mul_f32 v[56:57], v[56:57], v[220:221] op_sel_hi:[1,0]
	v_pk_mul_f32 v[54:55], v[54:55], v[220:221] op_sel_hi:[1,0]
	s_waitcnt lgkmcnt(0)
	v_mov_b32_e32 v84, v78
	s_movk_i32 s19, 0x2b00
	v_fma_f32 v62, v74, v62, v70
	global_store_dwordx4 v[82:83], v[58:61], off offset:16
	v_add_co_u32_e32 v82, vcc, 0x5000, v82
	v_mov_b32_e32 v85, v58
	s_nop 0
	v_addc_co_u32_e32 v83, vcc, 0, v83, vcc
	global_store_dwordx4 v[82:83], v[54:57], off offset:1552
	v_mov_b32_e32 v82, v54
	v_mov_b32_e32 v83, v66
	v_pk_mul_f32 v[82:83], v[82:83], v[84:85]
	v_mov_b32_e32 v58, v79
	v_add_f32_e32 v54, v83, v62
	v_add_f32_e32 v83, v82, v54
	v_mul_f32_e32 v54, 0xbfb8aa3b, v83
	v_exp_f32_e32 v54, v54
	v_mov_b32_e32 v82, v50
	v_fma_f32 v50, v75, v63, v71
	v_add_f32_e32 v54, 1.0, v54
	v_rcp_f32_e32 v221, v54
	v_mov_b32_e32 v54, v55
	v_mov_b32_e32 v55, v67
	v_pk_mul_f32 v[54:55], v[54:55], v[58:59]
	v_pk_mul_f32 v[82:83], v[82:83], v[220:221]
	v_add_f32_e32 v50, v55, v50
	v_add_f32_e32 v55, v54, v50
	v_mul_f32_e32 v50, 0xbfb8aa3b, v55
	v_exp_f32_e32 v50, v50
	v_mov_b32_e32 v54, v51
	v_fma_f32 v59, v76, v64, v72
	v_mul_f32_e32 v62, v82, v83
	v_add_f32_e32 v50, 1.0, v50
	v_rcp_f32_e32 v221, v50
	s_nop 0
	v_pk_mul_f32 v[50:51], v[54:55], v[220:221]
	s_nop 0
	v_mul_f32_e32 v58, v50, v51
	v_mov_b32_e32 v50, v56
	v_mov_b32_e32 v51, v68
	v_mov_b32_e32 v54, v80
	v_mov_b32_e32 v55, v60
	v_pk_mul_f32 v[50:51], v[50:51], v[54:55]
	v_mov_b32_e32 v60, v81
	v_add_f32_e32 v51, v51, v59
	v_add_f32_e32 v51, v50, v51
	v_mul_f32_e32 v50, 0xbfb8aa3b, v51
	v_exp_f32_e32 v50, v50
	v_fma_f32 v54, v77, v65, v73
	v_add_f32_e32 v50, 1.0, v50
	v_rcp_f32_e32 v221, v50
	v_mov_b32_e32 v50, v52
	v_pk_mul_f32 v[50:51], v[50:51], v[220:221]
	s_nop 0
	v_mul_f32_e32 v52, v50, v51
	v_mov_b32_e32 v50, v57
	v_mov_b32_e32 v51, v69
	v_pk_mul_f32 v[50:51], v[50:51], v[60:61]
	s_nop 0
	v_add_f32_e32 v51, v51, v54
	v_add_f32_e32 v51, v50, v51
	v_mul_f32_e32 v50, 0xbfb8aa3b, v51
	v_exp_f32_e32 v50, v50
	s_nop 0
	v_add_f32_e32 v50, 1.0, v50
	v_rcp_f32_e32 v221, v50
	v_mov_b32_e32 v50, v53
	v_pk_mul_f32 v[50:51], v[50:51], v[220:221]
	s_nop 0
	v_mul_f32_e32 v51, v50, v51
	v_cvt_pk_bf16_f32 v50, v62, v58
	v_cvt_pk_bf16_f32 v51, v52, v51
	v_mov_b64_e32 v[52:53], s[58:59]
	v_mad_i64_i32 v[52:53], s[36:37], v146, s19, v[52:53]
	v_lshl_add_u64 v[52:53], v[206:207], 1, v[52:53]
	global_store_dwordx2 v[52:53], v[50:51], off offset:8
	s_or_b64 exec, exec, s[26:27]
	s_and_saveexec_b64 s[26:27], s[40:41]
	s_cbranch_execnz .LBB0_1733

.LBB0_1741:
	v_mov_b64_e32 v[42:43], s[60:61]
	s_mov_b32 s19, 0xac00
	v_mad_i64_i32 v[42:43], s[36:37], v132, s19, v[42:43]
	v_lshl_add_u64 v[42:43], v[42:43], 0, v[154:155]
	v_add_co_u32_e32 v42, vcc, 0x5000, v42
	v_mov_b64_e32 v[50:51], s[66:67]
	s_nop 0
	v_addc_co_u32_e32 v43, vcc, 0, v43, vcc
	s_waitcnt vmcnt(3)
	v_mov_b32_e32 v46, v170
	v_mov_b32_e32 v47, v171
	v_mov_b32_e32 v48, v172
	v_mov_b32_e32 v49, v173
	v_mov_b32_e32 v42, v174
	v_mov_b32_e32 v43, v175
	v_mov_b32_e32 v44, v176
	v_mov_b32_e32 v45, v177
	s_and_saveexec_b64 s[100:101], s[44:45]
	v_add_u32_e32 v246, 0xffffe040, v241
	v_mul_u32_u24_e32 v246, 0xac00, v246
	v_lshl_add_u32 v246, v206, 2, v246
	v_mov_b32_e32 v247, 0
	v_add_u32_e32 v248, 0x5600, v246
	v_mov_b32_e32 v249, 0
	v_lshl_add_u64 v[246:247], v[246:247], 0, s[60:61]
	v_lshl_add_u64 v[248:249], v[248:249], 0, s[60:61]
	global_load_dwordx4 v[162:165], v[246:247], off offset:16
	global_load_dwordx4 v[166:169], v[248:249], off offset:16
	s_mov_b64 exec, s[100:101]
	v_mad_i64_i32 v[50:51], s[36:37], v131, s19, v[50:51]
	v_lshl_add_u64 v[50:51], v[50:51], 0, v[154:155]
	v_pk_mul_f32 v[40:41], v[40:41], v[216:217] op_sel_hi:[1,0]
	v_pk_mul_f32 v[38:39], v[38:39], v[216:217] op_sel_hi:[1,0]
	s_waitcnt lgkmcnt(0)
	v_mov_b32_e32 v52, v78
	s_movk_i32 s19, 0x2b00
	v_fma_f32 v46, v74, v46, v70
	global_store_dwordx4 v[50:51], v[42:45], off offset:16
	v_add_co_u32_e32 v50, vcc, 0x5000, v50
	v_mov_b32_e32 v53, v42
	s_nop 0
	v_addc_co_u32_e32 v51, vcc, 0, v51, vcc
	global_store_dwordx4 v[50:51], v[38:41], off offset:1552
	v_mov_b32_e32 v50, v38
	v_mov_b32_e32 v51, v66
	v_pk_mul_f32 v[50:51], v[50:51], v[52:53]
	v_mov_b32_e32 v42, v79
	v_add_f32_e32 v38, v51, v46
	v_add_f32_e32 v51, v50, v38
	v_mul_f32_e32 v38, 0xbfb8aa3b, v51
	v_exp_f32_e32 v38, v38
	v_mov_b32_e32 v50, v34
	v_fma_f32 v34, v75, v47, v71
	v_add_f32_e32 v38, 1.0, v38
	v_rcp_f32_e32 v217, v38
	v_mov_b32_e32 v38, v39
	v_mov_b32_e32 v39, v67
	v_pk_mul_f32 v[38:39], v[38:39], v[42:43]
	v_pk_mul_f32 v[50:51], v[50:51], v[216:217]
	v_add_f32_e32 v34, v39, v34
	v_add_f32_e32 v39, v38, v34
	v_mul_f32_e32 v34, 0xbfb8aa3b, v39
	v_exp_f32_e32 v34, v34
	v_mov_b32_e32 v38, v35
	v_fma_f32 v43, v76, v48, v72
	v_mul_f32_e32 v46, v50, v51
	v_add_f32_e32 v34, 1.0, v34
	v_rcp_f32_e32 v217, v34
	s_nop 0
	v_pk_mul_f32 v[34:35], v[38:39], v[216:217]
	s_nop 0
	v_mul_f32_e32 v42, v34, v35
	v_mov_b32_e32 v34, v40
	v_mov_b32_e32 v35, v68
	v_mov_b32_e32 v38, v80
	v_mov_b32_e32 v39, v44
	v_pk_mul_f32 v[34:35], v[34:35], v[38:39]
	v_mov_b32_e32 v44, v81
	v_add_f32_e32 v35, v35, v43
	v_add_f32_e32 v35, v34, v35
	v_mul_f32_e32 v34, 0xbfb8aa3b, v35
	v_exp_f32_e32 v34, v34
	v_fma_f32 v38, v77, v49, v73
	v_add_f32_e32 v34, 1.0, v34
	v_rcp_f32_e32 v217, v34
	v_mov_b32_e32 v34, v36
	v_pk_mul_f32 v[34:35], v[34:35], v[216:217]
	s_nop 0
	v_mul_f32_e32 v36, v34, v35
	v_mov_b32_e32 v34, v41
	v_mov_b32_e32 v35, v69
	v_pk_mul_f32 v[34:35], v[34:35], v[44:45]
	s_nop 0
	v_add_f32_e32 v35, v35, v38
	v_add_f32_e32 v35, v34, v35
	v_mul_f32_e32 v34, 0xbfb8aa3b, v35
	v_exp_f32_e32 v34, v34
	s_nop 0
	v_add_f32_e32 v34, 1.0, v34
	v_rcp_f32_e32 v217, v34
	v_mov_b32_e32 v34, v37
	v_pk_mul_f32 v[34:35], v[34:35], v[216:217]
	s_nop 0
	v_mul_f32_e32 v35, v34, v35
	v_cvt_pk_bf16_f32 v34, v46, v42
	v_cvt_pk_bf16_f32 v35, v36, v35
	v_mov_b64_e32 v[36:37], s[58:59]
	v_mad_i64_i32 v[36:37], s[36:37], v130, s19, v[36:37]
	v_lshl_add_u64 v[36:37], v[206:207], 1, v[36:37]
	global_store_dwordx2 v[36:37], v[34:35], off offset:8
	s_or_b64 exec, exec, s[26:27]
	s_and_saveexec_b64 s[26:27], s[44:45]
	s_cbranch_execnz .LBB0_1735

.LBB0_1743:
	v_mov_b64_e32 v[26:27], s[60:61]
	s_mov_b32 s19, 0xac00
	v_mad_i64_i32 v[26:27], s[36:37], v100, s19, v[26:27]
	v_lshl_add_u64 v[26:27], v[26:27], 0, v[154:155]
	v_add_co_u32_e32 v26, vcc, 0x5000, v26
	v_mov_b64_e32 v[34:35], s[66:67]
	s_nop 0
	v_addc_co_u32_e32 v27, vcc, 0, v27, vcc
	s_waitcnt vmcnt(3)
	v_mov_b32_e32 v30, v170
	v_mov_b32_e32 v31, v171
	v_mov_b32_e32 v32, v172
	v_mov_b32_e32 v33, v173
	v_mov_b32_e32 v26, v174
	v_mov_b32_e32 v27, v175
	v_mov_b32_e32 v28, v176
	v_mov_b32_e32 v29, v177
	s_and_saveexec_b64 s[100:101], s[48:49]
	v_add_u32_e32 v246, 0xffffe060, v241
	v_mul_u32_u24_e32 v246, 0xac00, v246
	v_lshl_add_u32 v246, v206, 2, v246
	v_mov_b32_e32 v247, 0
	v_add_u32_e32 v248, 0x5600, v246
	v_mov_b32_e32 v249, 0
	v_lshl_add_u64 v[246:247], v[246:247], 0, s[60:61]
	v_lshl_add_u64 v[248:249], v[248:249], 0, s[60:61]
	global_load_dwordx4 v[162:165], v[246:247], off offset:16
	global_load_dwordx4 v[166:169], v[248:249], off offset:16
	s_mov_b64 exec, s[100:101]
	v_mad_i64_i32 v[34:35], s[36:37], v99, s19, v[34:35]
	v_lshl_add_u64 v[34:35], v[34:35], 0, v[154:155]
	v_pk_mul_f32 v[24:25], v[24:25], v[212:213] op_sel_hi:[1,0]
	v_pk_mul_f32 v[22:23], v[22:23], v[212:213] op_sel_hi:[1,0]
	s_waitcnt lgkmcnt(0)
	v_mov_b32_e32 v36, v78
	s_movk_i32 s19, 0x2b00
	v_fma_f32 v30, v74, v30, v70
	global_store_dwordx4 v[34:35], v[26:29], off offset:16
	v_add_co_u32_e32 v34, vcc, 0x5000, v34
	v_mov_b32_e32 v37, v26
	s_nop 0
	v_addc_co_u32_e32 v35, vcc, 0, v35, vcc
	global_store_dwordx4 v[34:35], v[22:25], off offset:1552
	v_mov_b32_e32 v34, v22
	v_mov_b32_e32 v35, v66
	v_pk_mul_f32 v[34:35], v[34:35], v[36:37]
	v_mov_b32_e32 v26, v79
	v_add_f32_e32 v22, v35, v30
	v_add_f32_e32 v35, v34, v22
	v_mul_f32_e32 v22, 0xbfb8aa3b, v35
	v_exp_f32_e32 v22, v22
	v_mov_b32_e32 v34, v18
	v_fma_f32 v18, v75, v31, v71
	v_add_f32_e32 v22, 1.0, v22
	v_rcp_f32_e32 v213, v22
	v_mov_b32_e32 v22, v23
	v_mov_b32_e32 v23, v67
	v_pk_mul_f32 v[22:23], v[22:23], v[26:27]
	v_pk_mul_f32 v[34:35], v[34:35], v[212:213]
	v_add_f32_e32 v18, v23, v18
	v_add_f32_e32 v23, v22, v18
	v_mul_f32_e32 v18, 0xbfb8aa3b, v23
	v_exp_f32_e32 v18, v18
	v_mov_b32_e32 v22, v19
	v_fma_f32 v27, v76, v32, v72
	v_mul_f32_e32 v30, v34, v35
	v_add_f32_e32 v18, 1.0, v18
	v_rcp_f32_e32 v213, v18
	s_nop 0
	v_pk_mul_f32 v[18:19], v[22:23], v[212:213]
	s_nop 0
	v_mul_f32_e32 v26, v18, v19
	v_mov_b32_e32 v18, v24
	v_mov_b32_e32 v19, v68
	v_mov_b32_e32 v22, v80
	v_mov_b32_e32 v23, v28
	v_pk_mul_f32 v[18:19], v[18:19], v[22:23]
	v_mov_b32_e32 v28, v81
	v_add_f32_e32 v19, v19, v27
	v_add_f32_e32 v19, v18, v19
	v_mul_f32_e32 v18, 0xbfb8aa3b, v19
	v_exp_f32_e32 v18, v18
	v_fma_f32 v22, v77, v33, v73
	v_add_f32_e32 v18, 1.0, v18
	v_rcp_f32_e32 v213, v18
	v_mov_b32_e32 v18, v20
	v_pk_mul_f32 v[18:19], v[18:19], v[212:213]
	s_nop 0
	v_mul_f32_e32 v20, v18, v19
	v_mov_b32_e32 v18, v25
	v_mov_b32_e32 v19, v69
	v_pk_mul_f32 v[18:19], v[18:19], v[28:29]
	s_nop 0
	v_add_f32_e32 v19, v19, v22
	v_add_f32_e32 v19, v18, v19
	v_mul_f32_e32 v18, 0xbfb8aa3b, v19
	v_exp_f32_e32 v18, v18
	s_nop 0
	v_add_f32_e32 v18, 1.0, v18
	v_rcp_f32_e32 v213, v18
	v_mov_b32_e32 v18, v21
	v_pk_mul_f32 v[18:19], v[18:19], v[212:213]
	s_nop 0
	v_mul_f32_e32 v19, v18, v19
	v_cvt_pk_bf16_f32 v18, v30, v26
	v_cvt_pk_bf16_f32 v19, v20, v19
	v_mov_b64_e32 v[20:21], s[58:59]
	v_mad_i64_i32 v[20:21], s[36:37], v98, s19, v[20:21]
	v_lshl_add_u64 v[20:21], v[206:207], 1, v[20:21]
	global_store_dwordx2 v[20:21], v[18:19], off offset:8
	s_or_b64 exec, exec, s[26:27]
	s_and_saveexec_b64 s[26:27], s[48:49]
	s_cbranch_execnz .LBB0_1737

.LBB0_1745:
	v_mov_b64_e32 v[10:11], s[60:61]
	s_mov_b32 s19, 0xac00
	v_mad_i64_i32 v[10:11], s[36:37], v95, s19, v[10:11]
	v_lshl_add_u64 v[14:15], v[10:11], 0, v[154:155]
	v_add_co_u32_e32 v14, vcc, 0x5000, v14
	v_mov_b64_e32 v[18:19], s[66:67]
	s_nop 0
	v_addc_co_u32_e32 v15, vcc, 0, v15, vcc
	s_waitcnt vmcnt(3)
	v_mov_b32_e32 v10, v170
	v_mov_b32_e32 v11, v171
	v_mov_b32_e32 v12, v172
	v_mov_b32_e32 v13, v173
	v_mov_b32_e32 v14, v174
	v_mov_b32_e32 v15, v175
	v_mov_b32_e32 v16, v176
	v_mov_b32_e32 v17, v177
	v_mad_i64_i32 v[18:19], s[36:37], v93, s19, v[18:19]
	v_lshl_add_u64 v[18:19], v[18:19], 0, v[154:155]
	v_pk_mul_f32 v[8:9], v[8:9], v[208:209] op_sel_hi:[1,0]
	v_pk_mul_f32 v[6:7], v[6:7], v[208:209] op_sel_hi:[1,0]
	s_waitcnt lgkmcnt(0)
	v_mov_b32_e32 v20, v78
	s_movk_i32 s19, 0x2b00
	v_fma_f32 v10, v74, v10, v70
	v_fma_f32 v12, v76, v12, v72
	v_fmac_f32_e32 v73, v77, v13
	global_store_dwordx4 v[18:19], v[14:17], off offset:16
	v_add_co_u32_e32 v18, vcc, 0x5000, v18
	v_mov_b32_e32 v21, v14
	s_nop 0
	v_addc_co_u32_e32 v19, vcc, 0, v19, vcc
	global_store_dwordx4 v[18:19], v[6:9], off offset:1552
	v_mov_b32_e32 v18, v6
	v_mov_b32_e32 v19, v66
	v_pk_mul_f32 v[18:19], v[18:19], v[20:21]
	v_mov_b32_e32 v66, v7
	v_add_f32_e32 v6, v19, v10
	v_add_f32_e32 v19, v18, v6
	v_mul_f32_e32 v6, 0xbfb8aa3b, v19
	v_exp_f32_e32 v6, v6
	v_mov_b32_e32 v14, v79
	v_mov_b32_e32 v18, v2
	v_fma_f32 v2, v75, v11, v71
	v_add_f32_e32 v6, 1.0, v6
	v_rcp_f32_e32 v209, v6
	v_pk_mul_f32 v[6:7], v[66:67], v[14:15]
	v_pk_mul_f32 v[18:19], v[18:19], v[208:209]
	v_add_f32_e32 v2, v7, v2
	v_add_f32_e32 v7, v6, v2
	v_mul_f32_e32 v2, 0xbfb8aa3b, v7
	v_exp_f32_e32 v2, v2
	v_mov_b32_e32 v6, v3
	v_mul_f32_e32 v10, v18, v19
	v_add_f32_e32 v2, 1.0, v2
	v_rcp_f32_e32 v209, v2
	s_nop 0
	v_pk_mul_f32 v[2:3], v[6:7], v[208:209]
	s_nop 0
	v_mul_f32_e32 v11, v2, v3
	v_mov_b32_e32 v2, v8
	v_mov_b32_e32 v3, v68
	v_mov_b32_e32 v6, v80
	v_mov_b32_e32 v7, v16
	v_pk_mul_f32 v[2:3], v[2:3], v[6:7]
	v_mov_b32_e32 v68, v9
	v_add_f32_e32 v3, v3, v12
	v_add_f32_e32 v3, v2, v3
	v_mul_f32_e32 v2, 0xbfb8aa3b, v3
	v_exp_f32_e32 v2, v2
	v_mov_b32_e32 v16, v81
	v_add_f32_e32 v2, 1.0, v2
	v_rcp_f32_e32 v209, v2
	v_mov_b32_e32 v2, v4
	v_pk_mul_f32 v[2:3], v[2:3], v[208:209]
	s_nop 0
	v_mul_f32_e32 v4, v2, v3
	v_pk_mul_f32 v[2:3], v[68:69], v[16:17]
	s_nop 0
	v_add_f32_e32 v3, v3, v73
	v_add_f32_e32 v3, v2, v3
	v_mul_f32_e32 v2, 0xbfb8aa3b, v3
	v_exp_f32_e32 v2, v2
	s_nop 0
	v_add_f32_e32 v2, 1.0, v2
	v_rcp_f32_e32 v209, v2
	v_mov_b32_e32 v2, v5
	v_pk_mul_f32 v[2:3], v[2:3], v[208:209]
	s_nop 0
	v_mul_f32_e32 v3, v2, v3
	v_cvt_pk_bf16_f32 v2, v10, v11
	v_cvt_pk_bf16_f32 v3, v4, v3
	v_mov_b64_e32 v[4:5], s[58:59]
	v_mad_i64_i32 v[4:5], s[36:37], v91, s19, v[4:5]
	v_lshl_add_u64 v[4:5], v[206:207], 1, v[4:5]
	global_store_dwordx2 v[4:5], v[2:3], off offset:8
